# v39_swa2
# baseline (speedup 1.0000x reference)
; DI int crow(int i, int h) { return (i & 3) + 8 * (i >> 2) + 4 * h; }
; DI float ex2(float x) { return __builtin_amdgcn_exp2f(x); }
; DI f32x16 zero16() { f32x16 z; for (int i = 0; i < 16; ++i) z[i] = 0.f; return z; }
; DI void swa_item(const Ctx& c, const float* sinks, int qt, int hq, int lane) {
;     const int r = lane & 31, h = lane >> 5, t0 = qt * 32, t = t0 + r, g = hq >> 2;
;     bf16x8 qf[4];
;     { const bf16* Qp = c.P + (size_t)t * PP + hq * 64 + 8 * h;
; #pragma unroll
;       for (int ks = 0; ks < 4; ++ks) qf[ks] = *(const bf16x8*)(Qp + 16 * ks); }
;     const float sc2 = 0.125f * LOG2E, slope2 = ex2(-(float)(hq + 1)) * LOG2E, sink2 = sinks[hq] * LOG2E;
;     float m = sink2, l = 0.f; f32x16 o[2] = {zero16(), zero16()};
;     const int kstart = t0 >= 128 ? t0 - 128 : 0;
;     for (int key0 = kstart; key0 <= t0; key0 += 32) {
;         f32x16 x = qk_tile<64>(c.P + (size_t)(key0 + r) * PP + 2048 + g * 64 + 8 * h, qf);
; #pragma unroll
;         for (int i = 0; i < 16; ++i) { const int dist = t - (key0 + crow(i, h)); x[i] = ((unsigned)dist < 128u) ? x[i] * sc2 - slope2 * (float)dist : -INFINITY; }
.LBB0_1159:
	s_or_b64 exec, exec, s[8:9]
	v_readfirstlane_b32 s42, v0
	v_readlane_b32 s8, v244, 14
	s_cmp_ge_i32 s42, s8
	s_mov_b64 s[8:9], -1
	s_cbranch_scc1 .LBB0_1154
	v_readlane_b32 s8, v244, 13
	s_cmp_lt_i32 s42, s8
	s_cselect_b32 s8, s25, s24
	s_add_i32 s40, s42, s8
	s_cmpk_gt_i32 s40, 0x7ff
	s_mov_b64 s[8:9], -1
	s_cbranch_scc0 .LBB0_1164
	s_add_i32 s41, s40, 0xfffff800
	s_lshl_b32 s8, s41, 2
	s_and_b32 s9, s8, 0x7fffffe0
	s_and_b32 s43, s42, 7
	v_or_b32_e32 v0, s9, v151
	v_mov_b64_e32 v[2:3], s[26:27]
	v_mad_u64_u32 v[2:3], s[44:45], v0, s56, v[2:3]
	s_lshl_b32 s34, s43, 7
	v_lshl_add_u64 v[2:3], v[2:3], 0, s[34:35]
	v_lshl_add_u64 v[2:3], v[122:123], 1, v[2:3]
	s_add_i32 s34, s43, 1
	global_load_dwordx4 v[50:53], v[2:3], off
	global_load_dwordx4 v[54:57], v[2:3], off offset:32
	global_load_dwordx4 v[58:61], v[2:3], off offset:64
	global_load_dwordx4 v[62:65], v[2:3], off offset:96
	v_cvt_f32_ubyte0_e32 v2, s34
	v_exp_f32_e64 v2, -v2
	s_lshl_b32 s34, s43, 2
	s_lshl_b32 s8, s43, 6
	v_mov_b32_e32 v3, v1
	v_mul_f32_e32 v67, 0x3fb8aa3b, v2
	v_mov_b32_e32 v2, s34
	global_load_dword v2, v2, s[16:17]
	s_add_i32 s34, s9, 0xffffff80
	s_cmp_gt_u32 s41, 31
	s_cselect_b32 s41, s34, 0
	s_lshl_b32 s34, s42, 4
	s_and_b32 s34, s34, 64
	v_mov_b32_e32 v35, 0
	v_mov_b32_e32 v4, v35
	v_mov_b32_e32 v5, v35
	v_mov_b32_e32 v6, v35
	v_mov_b32_e32 v7, v35
	v_mov_b32_e32 v8, v35
	v_mov_b32_e32 v9, v35
	v_mov_b32_e32 v10, v35
	v_mov_b32_e32 v11, v35
	v_mov_b32_e32 v12, v35
	v_mov_b32_e32 v13, v35
	v_mov_b32_e32 v14, v35
	v_mov_b32_e32 v15, v35
	v_mov_b32_e32 v16, v35
	v_mov_b32_e32 v17, v35
	v_mov_b32_e32 v18, 0
	v_mov_b32_e32 v19, v35
	v_mov_b32_e32 v20, v35
	v_mov_b32_e32 v21, v35
	v_mov_b32_e32 v22, v35
	v_mov_b32_e32 v23, v35
	v_mov_b32_e32 v24, v35
	v_mov_b32_e32 v25, v35
	v_mov_b32_e32 v26, v35
	v_mov_b32_e32 v27, v35
	v_mov_b32_e32 v28, v35
	v_mov_b32_e32 v29, v35
	v_mov_b32_e32 v30, v35
	v_mov_b32_e32 v31, v35
	v_mov_b32_e32 v32, v35
	v_mov_b32_e32 v33, v35
	s_waitcnt vmcnt(0)
	v_mul_f32_e32 v70, 0x3fb8aa3b, v2
	v_or_b32_e32 v2, s34, v151
	v_lshlrev_b32_e32 v2, 6, v2
	v_lshl_add_u64 v[68:69], v[126:127], 0, v[2:3]
	v_add_u32_e32 v2, s9, v152
	v_subrev_u32_e32 v71, s41, v2
	s_lshl_b32 s34, s34, 1
	v_mov_b32_e32 v34, v70
	v_mov_b32_e32 v2, 0
	v_mov_b32_e32 v3, v35
	v_add_u32_e32 v228, s41, v151
	v_mov_b64_e32 v[206:207], s[26:27]
	v_mad_i64_i32 v[206:207], vcc, v228, s56, v[206:207]
	v_lshl_add_u64 v[206:207], v[206:207], 0, s[34:35]
	v_lshl_add_u64 v[206:207], v[122:123], 1, v[206:207]
	v_lshl_add_u64 v[228:229], v[206:207], 0, s[68:69]
	v_add_co_u32_e32 v206, vcc, s0, v206
	global_load_dwordx4 v[240:243], v[228:229], off offset:32
	s_nop 0
	v_addc_co_u32_e32 v207, vcc, 0, v207, vcc
	global_load_dwordx4 v[224:227], v[206:207], off
	global_load_dwordx4 v[198:201], v[228:229], off offset:64
	global_load_dwordx4 v[202:205], v[228:229], off offset:96
.LBB0_1162:
	v_mov_b32_e32 v78, v35
	v_mov_b32_e32 v79, v34
	s_ashr_i32 s42, s41, 5
	s_ashr_i32 s43, s42, 31
	s_lshl_b64 s[42:43], s[42:43], 16
	v_lshl_add_u64 v[206:207], v[68:69], 0, s[42:43]
	global_load_dwordx4 v[208:211], v[206:207], off
	global_load_dwordx4 v[212:215], v[206:207], off offset:16
	global_load_dwordx4 v[216:219], v[206:207], off offset:2048
	global_load_dwordx4 v[220:223], v[206:207], off offset:2064
	s_waitcnt vmcnt(4)
	v_mfma_f32_32x32x16_bf16 v[34:49], v[224:227], v[50:53], 0
	v_mfma_f32_32x32x16_bf16 v[34:49], v[240:243], v[54:57], v[34:49]
	v_mfma_f32_32x32x16_bf16 v[34:49], v[198:201], v[58:61], v[34:49]
	v_mfma_f32_32x32x16_bf16 v[34:49], v[202:205], v[62:65], v[34:49]
	v_add_u32_e32 v228, s41, v151
	v_add_u32_e32 v228, 32, v228
	v_mov_b64_e32 v[206:207], s[26:27]
	v_mad_i64_i32 v[206:207], vcc, v228, s56, v[206:207]
	v_lshl_add_u64 v[206:207], v[206:207], 0, s[34:35]
	v_lshl_add_u64 v[206:207], v[122:123], 1, v[206:207]
	v_lshl_add_u64 v[228:229], v[206:207], 0, s[68:69]
	v_add_co_u32_e32 v206, vcc, s0, v206
	global_load_dwordx4 v[240:243], v[228:229], off offset:32
	s_nop 0
	v_addc_co_u32_e32 v207, vcc, 0, v207, vcc
	global_load_dwordx4 v[224:227], v[206:207], off
	global_load_dwordx4 v[198:201], v[228:229], off offset:64
	global_load_dwordx4 v[202:205], v[228:229], off offset:96
	v_add_u32_e32 v74, v151, v71
	v_cvt_f32_u32_e32 v171, v74
	v_cmp_gt_u32_e32 vcc, s91, v74
	v_subrev_u32_e32 v71, 32, v71
	s_nop 7
	v_mov_b32_e32 v66, v34
	v_pk_mul_f32 v[72:73], v[66:67], v[170:171]
	v_mov_b32_e32 v66, v35
	v_sub_f32_e32 v34, v72, v73
	v_cndmask_b32_e32 v72, v237, v34, vcc
	v_add_u32_e32 v34, -1, v74
	v_cvt_f32_u32_e32 v171, v34
	v_cmp_gt_u32_e32 vcc, s91, v34
	v_pk_mul_f32 v[34:35], v[66:67], v[170:171]
	s_nop 0
	v_sub_f32_e32 v34, v34, v35
	v_cndmask_b32_e32 v73, v237, v34, vcc
	v_add_u32_e32 v34, -2, v74
	v_cvt_f32_u32_e32 v171, v34
	v_mov_b32_e32 v66, v36
	v_cmp_gt_u32_e32 vcc, s91, v34
	v_pk_mul_f32 v[34:35], v[66:67], v[170:171]
	s_nop 0
	v_sub_f32_e32 v34, v34, v35
	v_cndmask_b32_e32 v75, v237, v34, vcc
	v_add_u32_e32 v34, -3, v74
	v_cvt_f32_u32_e32 v171, v34
	v_mov_b32_e32 v66, v37
	v_cmp_gt_u32_e32 vcc, s91, v34
	v_pk_mul_f32 v[34:35], v[66:67], v[170:171]
	s_nop 0
	v_sub_f32_e32 v34, v34, v35
	v_cndmask_b32_e32 v76, v237, v34, vcc
	v_add_u32_e32 v34, -8, v74
	v_cvt_f32_u32_e32 v171, v34
	v_mov_b32_e32 v66, v38
	v_cmp_gt_u32_e32 vcc, s91, v34
	v_pk_mul_f32 v[34:35], v[66:67], v[170:171]
	s_nop 0
	v_sub_f32_e32 v34, v34, v35
	v_cndmask_b32_e32 v77, v237, v34, vcc
	v_add_u32_e32 v34, -9, v74
	v_cvt_f32_u32_e32 v171, v34
	v_mov_b32_e32 v66, v39
	v_cmp_gt_u32_e32 vcc, s91, v34
	v_pk_mul_f32 v[34:35], v[66:67], v[170:171]
	s_nop 0
	v_sub_f32_e32 v34, v34, v35
; DI int crow(int i, int h) { return (i & 3) + 8 * (i >> 2) + 4 * h; }
; DI float ex2(float x) { return __builtin_amdgcn_exp2f(x); }
; DI void both_halves(float x, float& lo, float& hi) { auto rr = __builtin_amdgcn_permlane32_swap(__float_as_uint(x), __float_as_uint(x), false, false); lo = __uint_as_float(rr[0]); hi = __uint_as_float(rr[1]); }
; template <int NDB> DI void osm_step(f32x16& x, float& m, float& l, f32x16 (&o)[NDB]) {
;     float tm = x[0];
; #pragma unroll
;     for (int i = 1; i < 16; ++i) tm = fmaxf(tm, x[i]);
;     float lo, hi; both_halves(tm, lo, hi); tm = fmaxf(lo, hi);
;     const float mn = fmaxf(m, tm), alpha = ex2(m - mn); m = mn;
;     float ps = 0.f;
; #pragma unroll
;     for (int i = 0; i < 16; ++i) { x[i] = ex2(x[i] - mn); ps += x[i]; }
;     l = l * alpha + ps;
; #pragma unroll
;     for (int db = 0; db < NDB; ++db) o[db] = o[db] * alpha;
; }
; DI void swa_item(const Ctx& c, const float* sinks, int qt, int hq, int lane) {
;     ...
;         for (int i = 0; i < 16; ++i) { const int dist = t - (key0 + crow(i, h)); x[i] = ((unsigned)dist < 128u) ? x[i] * sc2 - slope2 * (float)dist : -INFINITY; }
;         osm_step<2>(x, m, l, o);
;         pv_tile_p<64>(c.VT + ((size_t)(key0 >> 5) * 1024 + g * 64 + r) * 32 + 16 * h, x, o);
	v_cndmask_b32_e32 v80, v237, v34, vcc
	v_add_u32_e32 v34, -10, v74
	v_cvt_f32_u32_e32 v171, v34
	v_mov_b32_e32 v66, v40
	v_cmp_gt_u32_e32 vcc, s91, v34
	v_pk_mul_f32 v[34:35], v[66:67], v[170:171]
	s_nop 0
	v_sub_f32_e32 v34, v34, v35
	v_cndmask_b32_e32 v81, v237, v34, vcc
	v_add_u32_e32 v34, -11, v74
	v_cvt_f32_u32_e32 v171, v34
	v_mov_b32_e32 v66, v41
	v_cmp_gt_u32_e32 vcc, s91, v34
	v_pk_mul_f32 v[34:35], v[66:67], v[170:171]
	s_nop 0
	v_sub_f32_e32 v34, v34, v35
	v_cndmask_b32_e32 v82, v237, v34, vcc
	v_add_u32_e32 v34, -16, v74
	v_cvt_f32_u32_e32 v171, v34
	v_mov_b32_e32 v66, v42
	v_cmp_gt_u32_e32 vcc, s91, v34
	v_pk_mul_f32 v[34:35], v[66:67], v[170:171]
	s_nop 0
	v_sub_f32_e32 v34, v34, v35
	v_cndmask_b32_e32 v83, v237, v34, vcc
	v_subrev_u32_e32 v34, 17, v74
	v_cvt_f32_u32_e32 v171, v34
	v_mov_b32_e32 v66, v43
	v_cmp_gt_u32_e32 vcc, s91, v34
	v_pk_mul_f32 v[34:35], v[66:67], v[170:171]
	s_nop 0
	v_sub_f32_e32 v34, v34, v35
	v_cndmask_b32_e32 v84, v237, v34, vcc
	v_subrev_u32_e32 v34, 18, v74
	v_cvt_f32_u32_e32 v171, v34
	v_mov_b32_e32 v66, v44
	v_cmp_gt_u32_e32 vcc, s91, v34
	v_pk_mul_f32 v[34:35], v[66:67], v[170:171]
	s_nop 0
	v_sub_f32_e32 v34, v34, v35
	v_cndmask_b32_e32 v85, v237, v34, vcc
	v_subrev_u32_e32 v34, 19, v74
	v_cvt_f32_u32_e32 v171, v34
	v_mov_b32_e32 v66, v45
	v_cmp_gt_u32_e32 vcc, s91, v34
	v_pk_mul_f32 v[34:35], v[66:67], v[170:171]
	s_nop 0
	v_sub_f32_e32 v34, v34, v35
	v_cndmask_b32_e32 v86, v237, v34, vcc
	v_subrev_u32_e32 v34, 24, v74
	v_cvt_f32_u32_e32 v171, v34
	v_mov_b32_e32 v66, v46
	v_cmp_gt_u32_e32 vcc, s91, v34
	v_pk_mul_f32 v[34:35], v[66:67], v[170:171]
	s_nop 0
	v_sub_f32_e32 v34, v34, v35
	v_cndmask_b32_e32 v87, v237, v34, vcc
	v_subrev_u32_e32 v34, 25, v74
	v_cvt_f32_u32_e32 v171, v34
	v_mov_b32_e32 v66, v47
	v_cmp_gt_u32_e32 vcc, s91, v34
	v_pk_mul_f32 v[34:35], v[66:67], v[170:171]
	s_nop 0
	v_sub_f32_e32 v34, v34, v35
	v_cndmask_b32_e32 v88, v237, v34, vcc
	v_subrev_u32_e32 v34, 26, v74
	v_cvt_f32_u32_e32 v171, v34
	v_mov_b32_e32 v66, v48
	v_cmp_gt_u32_e32 vcc, s91, v34
	v_pk_mul_f32 v[34:35], v[66:67], v[170:171]
	s_nop 0
	v_sub_f32_e32 v34, v34, v35
	v_cndmask_b32_e32 v89, v237, v34, vcc
	v_subrev_u32_e32 v34, 27, v74
	v_cvt_f32_u32_e32 v171, v34
	v_mov_b32_e32 v66, v49
	v_cmp_gt_u32_e32 vcc, s91, v34
	v_pk_mul_f32 v[34:35], v[66:67], v[170:171]
	s_nop 0
	v_sub_f32_e32 v34, v34, v35
	v_cndmask_b32_e32 v35, v237, v34, vcc
	v_max_f32_e32 v34, v72, v73
	v_max3_f32 v34, v34, v75, v76
	v_max3_f32 v34, v34, v77, v80
	v_max3_f32 v34, v34, v81, v82
	v_max3_f32 v34, v34, v83, v84
	v_max3_f32 v34, v34, v85, v86
	v_max3_f32 v34, v34, v87, v88
	v_max3_f32 v34, v34, v89, v35
	v_mov_b32_e32 v36, v34
	s_nop 1
	v_permlane32_swap_b32_e32 v34, v36
	v_max3_f32 v34, v79, v34, v36
	v_sub_f32_e32 v36, v72, v34
	v_exp_f32_e32 v36, v36
	v_sub_f32_e32 v37, v73, v34
	v_exp_f32_e32 v37, v37
	v_sub_f32_e32 v35, v35, v34
	v_add_f32_e32 v38, 0, v36
	v_sub_f32_e32 v74, v79, v34
	v_add_f32_e32 v39, v37, v38
	v_sub_f32_e32 v38, v75, v34
	v_exp_f32_e32 v38, v38
	v_exp_f32_e32 v74, v74
	v_cvt_pk_bf16_f32 v36, v36, v37
	v_add_f32_e32 v40, v38, v39
	v_sub_f32_e32 v39, v76, v34
	v_exp_f32_e32 v39, v39
	v_pk_mul_f32 v[16:17], v[16:17], v[74:75] op_sel_hi:[1,0]
	v_pk_mul_f32 v[14:15], v[14:15], v[74:75] op_sel_hi:[1,0]
	v_pk_mul_f32 v[12:13], v[12:13], v[74:75] op_sel_hi:[1,0]
	v_add_f32_e32 v41, v39, v40
	v_sub_f32_e32 v40, v77, v34
	v_exp_f32_e32 v40, v40
	v_lshl_add_u64 v[76:77], v[68:69], 0, s[42:43]
	v_pk_mul_f32 v[10:11], v[10:11], v[74:75] op_sel_hi:[1,0]
	v_pk_mul_f32 v[8:9], v[8:9], v[74:75] op_sel_hi:[1,0]
	v_add_f32_e32 v42, v40, v41
	v_sub_f32_e32 v41, v80, v34
	v_exp_f32_e32 v41, v41
	v_pk_mul_f32 v[6:7], v[6:7], v[74:75] op_sel_hi:[1,0]
	v_pk_mul_f32 v[4:5], v[4:5], v[74:75] op_sel_hi:[1,0]
	v_pk_mul_f32 v[2:3], v[2:3], v[74:75] op_sel_hi:[1,0]
	v_add_f32_e32 v43, v41, v42
	v_sub_f32_e32 v42, v81, v34
	v_exp_f32_e32 v42, v42
	v_pk_mul_f32 v[32:33], v[32:33], v[74:75] op_sel_hi:[1,0]
	v_pk_mul_f32 v[30:31], v[30:31], v[74:75] op_sel_hi:[1,0]
	v_pk_mul_f32 v[28:29], v[28:29], v[74:75] op_sel_hi:[1,0]
	v_add_f32_e32 v44, v42, v43
	v_sub_f32_e32 v43, v82, v34
	v_exp_f32_e32 v43, v43
	v_pk_mul_f32 v[26:27], v[26:27], v[74:75] op_sel_hi:[1,0]
	v_pk_mul_f32 v[24:25], v[24:25], v[74:75] op_sel_hi:[1,0]
	v_pk_mul_f32 v[22:23], v[22:23], v[74:75] op_sel_hi:[1,0]
	v_add_f32_e32 v45, v43, v44
	v_sub_f32_e32 v44, v83, v34
	v_exp_f32_e32 v44, v44
	v_pk_mul_f32 v[20:21], v[20:21], v[74:75] op_sel_hi:[1,0]
	v_pk_mul_f32 v[18:19], v[18:19], v[74:75] op_sel_hi:[1,0]
	v_cvt_pk_bf16_f32 v37, v38, v39
	v_add_f32_e32 v46, v44, v45
	v_sub_f32_e32 v45, v84, v34
	v_exp_f32_e32 v45, v45
	v_cvt_pk_bf16_f32 v38, v40, v41
	v_cvt_pk_bf16_f32 v39, v42, v43
	s_add_i32 s42, s41, 32
	v_add_f32_e32 v47, v45, v46
	v_sub_f32_e32 v46, v85, v34
	v_exp_f32_e32 v46, v46
	v_cvt_pk_bf16_f32 v40, v44, v45
	s_cmp_lt_i32 s41, s9
	s_mov_b32 s41, s42
	v_add_f32_e32 v48, v46, v47
	v_sub_f32_e32 v47, v86, v34
	v_exp_f32_e32 v47, v47
	s_nop 0
	v_add_f32_e32 v49, v47, v48
	v_sub_f32_e32 v48, v87, v34
	v_exp_f32_e32 v48, v48
	v_cvt_pk_bf16_f32 v41, v46, v47
	v_add_f32_e32 v66, v48, v49
	v_sub_f32_e32 v49, v88, v34
	v_exp_f32_e32 v49, v49
	s_nop 0
	v_add_f32_e32 v72, v49, v66
	v_sub_f32_e32 v66, v89, v34
	v_exp_f32_e32 v66, v66
	v_cvt_pk_bf16_f32 v42, v48, v49
	v_add_f32_e32 v73, v66, v72
	v_exp_f32_e32 v72, v35
	s_nop 0
	v_add_f32_e32 v35, v72, v73
	v_fmac_f32_e32 v35, v78, v74
	v_cvt_pk_bf16_f32 v43, v66, v72
	s_waitcnt vmcnt(7)
	v_mfma_f32_32x32x16_bf16 v[2:17], v[208:211], v[36:39], v[2:17]
	s_waitcnt vmcnt(6)
	v_mfma_f32_32x32x16_bf16 v[2:17], v[212:215], v[40:43], v[2:17]
	s_waitcnt vmcnt(5)
	v_mfma_f32_32x32x16_bf16 v[18:33], v[216:219], v[36:39], v[18:33]
	s_waitcnt vmcnt(4)
	v_mfma_f32_32x32x16_bf16 v[18:33], v[220:223], v[40:43], v[18:33]
	s_cbranch_scc1 .LBB0_1162
; DI unsigned cvtpk(float lo, float hi) { typedef float f2 __attribute__((ext_vector_type(2))); typedef __bf16 b2 __attribute__((ext_vector_type(2))); f2 v = {lo, hi}; b2 b = __builtin_convertvector(v, b2); return __builtin_bit_cast(unsigned, b); }
; DI float ex2(float x) { return __builtin_amdgcn_exp2f(x); }
; DI void both_halves(float x, float& lo, float& hi) { auto rr = __builtin_amdgcn_permlane32_swap(__float_as_uint(x), __float_as_uint(x), false, false); lo = __uint_as_float(rr[0]); hi = __uint_as_float(rr[1]); }
; template <int NDB> DI void store_o(bf16* Yp, const f32x16 (&o)[NDB], float scale, int h) {
; #pragma unroll
;     for (int db = 0; db < NDB; ++db)
; #pragma unroll
;         for (int g4 = 0; g4 < 4; ++g4) { v2u w; w.x = cvtpk(o[db][4 * g4] * scale, o[db][4 * g4 + 1] * scale); w.y = cvtpk(o[db][4 * g4 + 2] * scale, o[db][4 * g4 + 3] * scale); *(v2u*)(Yp + 32 * db + 8 * g4 + 4 * h) = w; }
; }
; DI void swa_item(const Ctx& c, const float* sinks, int qt, int hq, int lane) {
;     ...
;     float lo, hi; both_halves(l, lo, hi);
;     const float lt = lo + hi + ex2(sink2 - m);
;     store_o<2>(c.Y + (size_t)t * 512 + hq * 64, o, 1.f / lt, h);
	v_sub_f32_e32 v34, v70, v34
	v_exp_f32_e32 v34, v34
	v_mov_b32_e32 v36, v35
	s_nop 1
	v_permlane32_swap_b32_e32 v35, v36
	v_add_f32_e32 v35, v35, v36
	v_add_f32_e32 v36, v34, v35
	v_lshlrev_b64 v[34:35], 10, v[0:1]
	s_lshl_b32 s34, s8, 1
	v_div_scale_f32 v0, s[8:9], v36, v36, 1.0
	v_rcp_f32_e32 v37, v0
	v_lshl_add_u64 v[34:35], s[12:13], 0, v[34:35]
	v_lshl_add_u64 v[34:35], v[34:35], 0, s[34:35]
	v_lshl_add_u64 v[34:35], v[124:125], 1, v[34:35]
	v_fma_f32 v38, -v0, v37, 1.0
	v_fmac_f32_e32 v37, v38, v37
	v_div_scale_f32 v38, vcc, 1.0, v36, 1.0
	v_mul_f32_e32 v39, v38, v37
	v_fma_f32 v40, -v0, v39, v38
	v_fmac_f32_e32 v39, v40, v37
	v_fma_f32 v0, -v0, v39, v38
	v_div_fmas_f32 v0, v0, v37, v39
	v_div_fixup_f32 v0, v0, v36, 1.0
	v_pk_mul_f32 v[2:3], v[2:3], v[0:1] op_sel_hi:[1,0]
	v_pk_mul_f32 v[4:5], v[4:5], v[0:1] op_sel_hi:[1,0]
	v_cvt_pk_bf16_f32 v2, v2, v3
	v_cvt_pk_bf16_f32 v3, v4, v5
	global_store_dwordx2 v[34:35], v[2:3], off
	v_pk_mul_f32 v[2:3], v[6:7], v[0:1] op_sel_hi:[1,0]
	v_pk_mul_f32 v[4:5], v[8:9], v[0:1] op_sel_hi:[1,0]
	v_cvt_pk_bf16_f32 v2, v2, v3
	v_cvt_pk_bf16_f32 v3, v4, v5
	global_store_dwordx2 v[34:35], v[2:3], off offset:16
	v_pk_mul_f32 v[2:3], v[10:11], v[0:1] op_sel_hi:[1,0]
	v_pk_mul_f32 v[4:5], v[12:13], v[0:1] op_sel_hi:[1,0]
	v_cvt_pk_bf16_f32 v2, v2, v3
	v_cvt_pk_bf16_f32 v3, v4, v5
	global_store_dwordx2 v[34:35], v[2:3], off offset:32
	v_pk_mul_f32 v[2:3], v[14:15], v[0:1] op_sel_hi:[1,0]
	v_pk_mul_f32 v[4:5], v[16:17], v[0:1] op_sel_hi:[1,0]
	v_cvt_pk_bf16_f32 v2, v2, v3
	v_cvt_pk_bf16_f32 v3, v4, v5
	global_store_dwordx2 v[34:35], v[2:3], off offset:48
	v_pk_mul_f32 v[2:3], v[18:19], v[0:1] op_sel_hi:[1,0]
	v_pk_mul_f32 v[4:5], v[20:21], v[0:1] op_sel_hi:[1,0]
	v_cvt_pk_bf16_f32 v2, v2, v3
	v_cvt_pk_bf16_f32 v3, v4, v5
	global_store_dwordx2 v[34:35], v[2:3], off offset:64
	v_pk_mul_f32 v[2:3], v[22:23], v[0:1] op_sel_hi:[1,0]
	v_pk_mul_f32 v[4:5], v[24:25], v[0:1] op_sel_hi:[1,0]
	v_cvt_pk_bf16_f32 v2, v2, v3
	v_cvt_pk_bf16_f32 v3, v4, v5
	global_store_dwordx2 v[34:35], v[2:3], off offset:80
	v_pk_mul_f32 v[2:3], v[26:27], v[0:1] op_sel_hi:[1,0]
	v_pk_mul_f32 v[4:5], v[28:29], v[0:1] op_sel_hi:[1,0]
	v_cvt_pk_bf16_f32 v2, v2, v3
	v_cvt_pk_bf16_f32 v3, v4, v5
	global_store_dwordx2 v[34:35], v[2:3], off offset:96
	v_pk_mul_f32 v[2:3], v[30:31], v[0:1] op_sel_hi:[1,0]
	v_pk_mul_f32 v[4:5], v[32:33], v[0:1] op_sel_hi:[1,0]
	v_cvt_pk_bf16_f32 v2, v2, v3
	v_cvt_pk_bf16_f32 v3, v4, v5
	s_mov_b64 s[8:9], 0
	s_mov_b32 s44, s19
	global_store_dwordx2 v[34:35], v[2:3], off offset:112
